# S5 output C.x: four X-fragment LDS reads issued together into separate register quads (counted waits) instead of one behind each MFMA
# speedup vs baseline: 1.0063x; 1.0063x over previous
; #define LAS __attribute__((address_space(3)))
; __device__ __forceinline__ unsigned f2bf(float f) { unsigned u = __builtin_bit_cast(unsigned, f); return (u + 0x7fffu + ((u >> 16) & 1u)) >> 16; }
; __device__ __forceinline__ float bf1(bf16 h) { return __uint_as_float(((unsigned)h) << 16); }
; __device__ __forceinline__ float siluf(float v) { return v * sigmf(v); }
; __device__ __forceinline__ float gelu_tanh(float y) { const float z = 0.7978845608028654f * (y + 0.044715f * y * y * y); return y * sigmf(2.f * z); }
; template <bool OUT> __device__ __forceinline__ void s5_item(const PA& a, LAS unsigned char* lds, int layer, int item, int wave, int lane) {
;     ...
;         if (OUT) {
;             f32x4 acc = {0.f, 0.f, 0.f, 0.f};
; #pragma unroll
;             for (int ks = 0; ks < 4; ++ks) { const bf16x8 xa = *(const LAS bf16x8*)(X + l15 * 136 + ks * 32 + quad * 8); acc = __builtin_amdgcn_mfma_f32_16x16x32_bf16(xa, cfr[ks], acc, 0, 0, 0); }
; #pragma unroll
;             for (int j = 0; j < 4; ++j) { const size_t row = row0 + quad * 4 + j;
;                 const float u = bf1(ue[j]);
;                 const float yg = gelu_tanh(acc[j] + dsk * u);
;                 ((bf16*)(a.ws + WS_YG))[row * 256 + g * 16 + l15] = (bf16)f2bf(yg);
;                 ((bf16*)(a.ws + WS_YGS))[row * 256 + g * 16 + l15] = (bf16)f2bf(yg * siluf(bf1(se[j]))); }
.LBB0_697:
	ds_read_b128 v[84:87], v103 offset:8448
	ds_read_b128 v[148:151], v103 offset:8512
	ds_read_b128 v[204:207], v103 offset:8576
	ds_read_b128 v[208:211], v103 offset:8640
	v_lshlrev_b32_e32 v138, 16, v138
	v_lshlrev_b32_e32 v137, 16, v137
	v_lshlrev_b32_e32 v134, 16, v134
	v_lshlrev_b32_e32 v133, 16, v133
	v_lshlrev_b32_e32 v135, 16, v135
	s_add_i32 s10, s10, 1
	v_lshl_add_u64 v[126:127], v[126:127], 0, s[18:19]
	s_waitcnt lgkmcnt(3)
	v_mfma_f32_16x16x32_bf16 v[84:87], v[84:87], v[32:35], 0
	v_lshl_add_u64 v[128:129], v[128:129], 0, s[18:19]
	s_cmp_lg_u32 s10, 8
	s_waitcnt lgkmcnt(2)
	v_mfma_f32_16x16x32_bf16 v[84:87], v[148:151], v[36:39], v[84:87]
	s_waitcnt lgkmcnt(1)
	v_mfma_f32_16x16x32_bf16 v[84:87], v[204:207], v[40:43], v[84:87]
	s_waitcnt lgkmcnt(0)
	v_mfma_f32_16x16x32_bf16 v[84:87], v[208:211], v[44:47], v[84:87]
	v_lshl_add_u64 v[148:149], s[68:69], 0, v[130:131]
	v_add_co_u32_e32 v150, vcc, s65, v148
	s_nop 5
	v_fma_f32 v84, v111, v138, v84
	v_mul_f32_e32 v138, 0x3d372713, v84
	v_mul_f32_e32 v138, v84, v138
	v_fma_f32 v138, v84, v138, v84
	v_mul_f32_e32 v138, 0x3f4c422a, v138
	v_add_f32_e32 v138, v138, v138
	v_mul_f32_e32 v138, 0xbfb8aa3b, v138
	v_exp_f32_e32 v138, v138
	v_addc_co_u32_e32 v151, vcc, 0, v149, vcc
	v_add_co_u32_e32 v148, vcc, s72, v148
	v_add_f32_e32 v138, 1.0, v138
	v_rcp_f32_e32 v138, v138
	v_addc_co_u32_e32 v149, vcc, 0, v149, vcc
	v_fma_f32 v86, v111, v134, v86
	v_mul_f32_e32 v84, v84, v138
	v_bfe_u32 v138, v84, 16, 1
	v_add3_u32 v138, v84, v138, s73
	global_store_short_d16_hi v[150:151], v138, off
	v_mul_f32_e32 v138, 0xbfb8aa3b, v137
	v_exp_f32_e32 v138, v138
	v_mul_f32_e32 v134, 0x3d372713, v86
	v_mul_f32_e32 v134, v86, v134
	v_fma_f32 v134, v86, v134, v86
	v_add_f32_e32 v138, 1.0, v138
	v_rcp_f32_e32 v138, v138
	v_mul_f32_e32 v134, 0x3f4c422a, v134
	v_add_f32_e32 v134, v134, v134
	v_mul_f32_e32 v134, 0xbfb8aa3b, v134
	v_mul_f32_e32 v137, v138, v137
	v_mul_f32_e32 v84, v137, v84
	v_bfe_u32 v137, v84, 16, 1
	v_add3_u32 v84, v84, v137, s73
	global_store_short_d16_hi v[148:149], v84, off
	v_lshlrev_b32_e32 v84, 16, v136
	v_fma_f32 v84, v111, v84, v85
	v_mul_f32_e32 v85, 0x3d372713, v84
	v_mul_f32_e32 v85, v84, v85
	v_fma_f32 v85, v84, v85, v84
	v_mul_f32_e32 v85, 0x3f4c422a, v85
	v_add_f32_e32 v85, v85, v85
	v_mul_f32_e32 v85, 0xbfb8aa3b, v85
	v_exp_f32_e32 v85, v85
	v_exp_f32_e32 v134, v134
	v_lshl_add_u64 v[130:131], v[130:131], 0, s[28:29]
	v_add_f32_e32 v85, 1.0, v85
	v_rcp_f32_e32 v85, v85
	v_add_f32_e32 v134, 1.0, v134
	v_rcp_f32_e32 v134, v134
	v_mul_f32_e32 v138, v84, v85
	v_bfe_u32 v84, v138, 16, 1
	v_add3_u32 v147, v138, v84, s73
	v_lshl_add_u64 v[84:85], s[68:69], 0, v[124:125]
	v_mul_f32_e32 v86, v86, v134
	v_add_co_u32_e32 v136, vcc, s65, v84
	v_bfe_u32 v134, v86, 16, 1
	s_nop 0
	v_addc_co_u32_e32 v137, vcc, 0, v85, vcc
	v_add3_u32 v134, v86, v134, s73
	global_store_short_d16_hi v[136:137], v134, off offset:1024
	v_mul_f32_e32 v134, 0xbfb8aa3b, v133
	v_exp_f32_e32 v134, v134
	v_add_co_u32_e32 v84, vcc, s72, v84
	global_store_short_d16_hi v[136:137], v147, off offset:512
	v_add_f32_e32 v134, 1.0, v134
	v_rcp_f32_e32 v134, v134
	v_addc_co_u32_e32 v85, vcc, 0, v85, vcc
	v_mul_f32_e32 v147, 0xbfb8aa3b, v135
	v_mul_f32_e32 v133, v134, v133
	v_mul_f32_e32 v86, v133, v86
	v_bfe_u32 v133, v86, 16, 1
	v_add3_u32 v86, v86, v133, s73
	global_store_short_d16_hi v[84:85], v86, off offset:1024
	v_lshlrev_b32_e32 v86, 16, v132
	v_fmac_f32_e32 v87, v111, v86
	v_mul_f32_e32 v86, 0x3d372713, v87
	v_mul_f32_e32 v86, v87, v86
	v_fma_f32 v86, v87, v86, v87
	v_mul_f32_e32 v86, 0x3f4c422a, v86
	v_add_f32_e32 v86, v86, v86
	v_mul_f32_e32 v86, 0xbfb8aa3b, v86
	v_exp_f32_e32 v86, v86
	v_exp_f32_e32 v147, v147
	v_lshl_add_u64 v[124:125], v[124:125], 0, s[28:29]
	s_waitcnt vmcnt(7)
	v_mov_b32_e32 v133, v144
	v_add_f32_e32 v86, 1.0, v86
	v_rcp_f32_e32 v86, v86
	v_add_f32_e32 v147, 1.0, v147
	v_rcp_f32_e32 v147, v147
	v_mov_b32_e32 v134, v143
	v_mul_f32_e32 v86, v87, v86
	v_bfe_u32 v87, v86, 16, 1
	v_add3_u32 v87, v86, v87, s73
	global_store_short_d16_hi v[136:137], v87, off offset:1536
	v_lshlrev_b32_e32 v87, 16, v117
	v_mul_f32_e32 v117, 0xbfb8aa3b, v87
	v_exp_f32_e32 v117, v117
	v_mul_f32_e32 v135, v147, v135
	v_mul_f32_e32 v135, v135, v138
	v_bfe_u32 v138, v135, 16, 1
	v_add_f32_e32 v117, 1.0, v117
	v_rcp_f32_e32 v117, v117
	v_add3_u32 v135, v135, v138, s73
	global_store_short_d16_hi v[84:85], v135, off offset:512
	v_mov_b32_e32 v137, v140
	v_mul_f32_e32 v87, v117, v87
	v_mul_f32_e32 v86, v87, v86
	v_bfe_u32 v87, v86, 16, 1
	v_add3_u32 v86, v86, v87, s73
	v_mov_b32_e32 v135, v142
	s_waitcnt vmcnt(7)
	v_mov_b32_e32 v117, v146
	v_mov_b32_e32 v138, v139
	v_mov_b32_e32 v136, v141
	v_mov_b32_e32 v132, v145
	global_store_short_d16_hi v[84:85], v86, off offset:1536
	s_cbranch_scc0 .LBB0_673
